# P2/P4 stores all write-through so the barriers after them skip the L2 write-back fence; + early acquire invalidate etc.
# baseline (speedup 1.0000x reference)
; __device__ __forceinline__ unsigned f2bf(float f) { unsigned u = __builtin_bit_cast(unsigned, f); return (u + 0x7fffu + ((u >> 16) & 1u)) >> 16; }
; __device__ __forceinline__ void scan_item(const Params& p, LAS unsigned char* lds, int bh, int tid, int lane, int wave) {
;     ...
;     u32x4* qa = (u32x4*)(p.ws + WS_QAUG) + (size_t)bh * S_ + 4 * tid; u32x4* ka = (u32x4*)(p.ws + WS_KAUG) + (size_t)bh * S_ + 4 * tid;
; #pragma unroll
;     for (int i = 0; i < 4; ++i) { const float F = (off + a[i]) * LOG2E;
;         const unsigned hi = f2bf(F); const float r1 = F - bf2f(hi); const unsigned mid = f2bf(r1); const float r2 = r1 - bf2f(mid); const unsigned lo = f2bf(r2);
;         u32x4 q, k; q.x = hi | (mid << 16); q.y = lo | (0x3F80u << 16); q.z = 0x3F803F80u; q.w = 0u;
;         k.x = 0x3F803F80u; k.y = 0x3F80u | ((hi ^ 0x8000u) << 16); k.z = (mid ^ 0x8000u) | ((lo ^ 0x8000u) << 16); k.w = 0u;
;         qa[i] = q; ka[i] = k; }
;     __syncthreads();
.LBB0_264:
	s_ashr_i32 s3, s2, 31
	s_lshl_b64 s[4:5], s[2:3], 15
	s_add_u32 s4, s36, s4
	v_add_f32_e32 v4, v4, v3
	v_lshlrev_b32_e32 v6, 4, v96
	v_mov_b32_e32 v7, 0
	s_addc_u32 s5, s37, s5
	v_mul_f32_e32 v5, 0x3fb8aa3b, v4
	v_lshl_add_u64 v[12:13], s[4:5], 0, v[6:7]
	v_bfe_u32 v6, v5, 16, 1
	s_movk_i32 s1, 0x7fff
	v_add3_u32 v8, v5, v6, s1
	s_mov_b32 s0, 0x3fb8aa3b
	v_and_b32_e32 v5, 0xffff0000, v8
	v_fma_f32 v4, v4, s0, -v5
	v_bfe_u32 v5, v4, 16, 1
	v_add3_u32 v5, v4, v5, s1
	v_lshrrev_b32_e32 v9, 16, v5
	v_and_b32_e32 v5, 0xffff0000, v5
	v_sub_f32_e32 v4, v4, v5
	v_bfe_u32 v6, v4, 16, 1
	s_mov_b64 s[4:5], 0x200000
	v_add3_u32 v10, v4, v6, s1
	v_mov_b32_e32 v20, 1.0
	v_lshl_add_u64 v[14:15], v[12:13], 0, s[4:5]
	s_mov_b64 s[4:5], 0x400000
	v_or_b32_sdwa v11, v5, v8 dst_sel:DWORD dst_unused:UNUSED_PAD src0_sel:DWORD src1_sel:WORD_1
	v_or_b32_sdwa v18, v10, v20 dst_sel:DWORD dst_unused:UNUSED_PAD src0_sel:WORD_1 src1_sel:DWORD
	s_mov_b32 s11, 0
	s_mov_b32 s10, 0x3f803f80
	v_mov_b64_e32 v[4:5], s[8:9]
	s_mov_b32 s3, 0x80003f80
	v_mov_b32_e32 v21, 0xffff0000
	v_lshl_add_u64 v[16:17], v[12:13], 0, s[4:5]
	v_mov_b64_e32 v[6:7], s[10:11]
	v_mov_b32_e32 v5, v18
	v_bitop3_b32 v18, v8, s3, v21 bitop3:0x6c
	v_and_b32_e32 v8, 0xffff0000, v10
	s_mov_b32 s4, 0x80008000
	s_mov_b32 s8, s10
	v_mov_b32_e32 v4, v11
	v_bitop3_b32 v19, v8, s4, v9 bitop3:0x36
	v_mov_b64_e32 v[8:9], s[8:9]
	s_mov_b32 s5, 0x200000
	v_mov_b64_e32 v[10:11], s[10:11]
	v_mov_b32_e32 v9, v18
	v_add_co_u32_e32 v18, vcc, s5, v12
	v_mov_b32_e32 v10, v19
	s_nop 0
	v_addc_co_u32_e32 v19, vcc, 0, v13, vcc
	s_mov_b32 s5, 0x400000
	global_store_dwordx4 v[18:19], v[4:7], off sc1
	v_add_f32_e32 v2, v2, v3
	v_add_f32_e32 v1, v1, v3
	v_add_co_u32_e32 v4, vcc, s5, v12
	v_add_f32_e32 v0, v0, v3
	s_nop 0
	v_addc_co_u32_e32 v5, vcc, 0, v13, vcc
	global_store_dwordx4 v[4:5], v[8:11], off sc1
	v_mul_f32_e32 v4, 0x3fb8aa3b, v2
	v_bfe_u32 v5, v4, 16, 1
	v_add3_u32 v8, v4, v5, s1
	v_and_b32_e32 v4, 0xffff0000, v8
	v_fma_f32 v2, v2, s0, -v4
	v_bfe_u32 v4, v2, 16, 1
	v_add3_u32 v4, v2, v4, s1
	v_lshrrev_b32_e32 v9, 16, v4
	v_and_b32_e32 v4, 0xffff0000, v4
	v_sub_f32_e32 v2, v2, v4
	v_bfe_u32 v5, v2, 16, 1
	v_add3_u32 v2, v2, v5, s1
	v_or_b32_sdwa v10, v4, v8 dst_sel:DWORD dst_unused:UNUSED_PAD src0_sel:DWORD src1_sel:WORD_1
	v_or_b32_sdwa v11, v2, v20 dst_sel:DWORD dst_unused:UNUSED_PAD src0_sel:WORD_1 src1_sel:DWORD
	v_mov_b64_e32 v[4:5], s[8:9]
	v_and_b32_e32 v2, 0xffff0000, v2
	v_mov_b32_e32 v4, v10
	v_mov_b32_e32 v5, v11
	v_bitop3_b32 v12, v8, s3, v21 bitop3:0x6c
	v_bitop3_b32 v2, v2, s4, v9 bitop3:0x36
	v_mov_b64_e32 v[8:9], s[8:9]
	v_mov_b64_e32 v[10:11], s[10:11]
	v_mov_b64_e32 v[6:7], s[10:11]
	v_mov_b32_e32 v10, v2
	v_mul_f32_e32 v2, 0x3fb8aa3b, v1
	v_mov_b32_e32 v9, v12
	global_store_dwordx4 v[14:15], v[4:7], off offset:16 sc1
	global_store_dwordx4 v[16:17], v[8:11], off offset:16 sc1
	s_nop 0
	v_bfe_u32 v4, v2, 16, 1
	v_add3_u32 v2, v2, v4, s1
	v_and_b32_e32 v4, 0xffff0000, v2
	v_fma_f32 v1, v1, s0, -v4
	v_bfe_u32 v4, v1, 16, 1
	v_add3_u32 v4, v1, v4, s1
	v_lshrrev_b32_e32 v8, 16, v4
	v_and_b32_e32 v4, 0xffff0000, v4
	v_sub_f32_e32 v1, v1, v4
	v_bfe_u32 v5, v1, 16, 1
	v_add3_u32 v1, v1, v5, s1
	v_or_b32_sdwa v9, v4, v2 dst_sel:DWORD dst_unused:UNUSED_PAD src0_sel:DWORD src1_sel:WORD_1
	v_or_b32_sdwa v10, v1, v20 dst_sel:DWORD dst_unused:UNUSED_PAD src0_sel:WORD_1 src1_sel:DWORD
	v_mov_b64_e32 v[4:5], s[8:9]
	v_and_b32_e32 v1, 0xffff0000, v1
	v_mov_b32_e32 v4, v9
	v_mov_b32_e32 v5, v10
	v_bitop3_b32 v1, v1, s4, v8 bitop3:0x36
	v_mov_b64_e32 v[8:9], s[8:9]
	v_mov_b64_e32 v[10:11], s[10:11]
	v_bitop3_b32 v2, v2, s3, v21 bitop3:0x6c
	v_mov_b32_e32 v10, v1
	v_mul_f32_e32 v1, 0x3fb8aa3b, v0
	v_mov_b64_e32 v[6:7], s[10:11]
	v_mov_b32_e32 v9, v2
	v_bfe_u32 v2, v1, 16, 1
	global_store_dwordx4 v[14:15], v[4:7], off offset:32 sc1
	global_store_dwordx4 v[16:17], v[8:11], off offset:32 sc1
	s_nop 0
	v_add3_u32 v4, v1, v2, s1
	v_and_b32_e32 v1, 0xffff0000, v4
	v_fma_f32 v0, v0, s0, -v1
	v_bfe_u32 v1, v0, 16, 1
	v_add3_u32 v1, v0, v1, s1
	v_lshrrev_b32_e32 v5, 16, v1
	v_and_b32_e32 v1, 0xffff0000, v1
	v_sub_f32_e32 v0, v0, v1
	v_bfe_u32 v2, v0, 16, 1
	v_add3_u32 v6, v0, v2, s1
	v_or_b32_sdwa v7, v1, v4 dst_sel:DWORD dst_unused:UNUSED_PAD src0_sel:DWORD src1_sel:WORD_1
	v_or_b32_sdwa v8, v6, v20 dst_sel:DWORD dst_unused:UNUSED_PAD src0_sel:WORD_1 src1_sel:DWORD
	v_mov_b64_e32 v[0:1], s[8:9]
	v_mov_b32_e32 v1, v8
	v_bitop3_b32 v8, v4, s3, v21 bitop3:0x6c
	v_and_b32_e32 v4, 0xffff0000, v6
	v_mov_b32_e32 v0, v7
	v_bitop3_b32 v9, v4, s4, v5 bitop3:0x36
	v_mov_b64_e32 v[4:5], s[8:9]
	v_mov_b64_e32 v[2:3], s[10:11]
	v_mov_b64_e32 v[6:7], s[10:11]
	v_mov_b32_e32 v5, v8
	v_mov_b32_e32 v6, v9
	global_store_dwordx4 v[14:15], v[0:3], off offset:48 sc1
	global_store_dwordx4 v[16:17], v[4:7], off offset:48 sc1
	s_barrier

; __device__ __forceinline__ unsigned f2bf(float f) { unsigned u = __builtin_bit_cast(unsigned, f); return (u + 0x7fffu + ((u >> 16) & 1u)) >> 16; }
;     __device__ __forceinline__ void operator()(const f32x4 (&acc)[2][2][4][2], const pg8::Unit& u, int wr, int wc, int fr, int fq) const {
;     ...
;         } else if (pn < 6) {
;             const int head = 4 * (pn & 1) + wc, b = u.pm >> 3;
;             bf16_t* vb = Vt + (size_t)((b * 8 + head) * 64) * S_;
; #pragma unroll
;             for (int ai = 0; ai < 2; ++ai)
; #pragma unroll
;                 for (int m = 0; m < 4; ++m) { const int t = (row0 + ai * 128 + m * 16) & (S_ - 1);
;                     const int tp = (t & ~15) | (((t >> 2) & 1) << 3) | (((t >> 3) & 1) << 2) | (t & 3);
; #pragma unroll
;                     for (int bj = 0; bj < 2; ++bj)
; #pragma unroll
;                         for (int n = 0; n < 2; ++n) { const f32x4 a = acc[ai][bj][m][n]; const int d = 32 * bj + 8 * fq + 4 * n;
;                             vb[(unsigned)((d + 0) * S_ + tp)] = (bf16_t)f2bf(a.x); vb[(unsigned)((d + 1) * S_ + tp)] = (bf16_t)f2bf(a.y);
;                             vb[(unsigned)((d + 2) * S_ + tp)] = (bf16_t)f2bf(a.z); vb[(unsigned)((d + 3) * S_ + tp)] = (bf16_t)f2bf(a.w); }
;                 }
.LBB0_286:
	s_andn2_b64 vcc, exec, s[14:15]
	s_cbranch_vccnz .LBB0_288
	s_lshl_b32 s0, s21, 2
	s_and_b32 s0, s0, 4
	s_and_b32 s1, s20, 0x3fffff8
	s_or_b32 s0, s1, s0
	s_or_b32 s0, s0, s67
	s_lshl_b32 s14, s0, 6
	s_ashr_i32 s15, s14, 31
	s_lshl_b64 s[14:15], s[14:15], 12
	s_add_u32 s14, s65, s14
	s_addc_u32 s15, s66, s15
	s_and_b32 s0, s43, 0x7c0
	s_lshl_b32 s0, s0, 1
	v_and_b32_e32 v136, 12, v208
	v_and_b32_e32 v147, 3, v208
	v_lshlrev_b32_e32 v136, 13, v136
	v_lshl_or_b32 v136, v147, 12, v136
	v_bfe_u32 v147, v208, 4, 1
	v_lshl_or_b32 v136, v147, 4, v136
	v_bfe_u32 v147, v208, 5, 1
	v_lshl_or_b32 v136, v147, 5, v136
	v_add_u32_e32 v136, s0, v136
	v_add_u32_e32 v148, 0x4000, v136
	v_add_u32_e32 v149, 0x20000, v136
	v_add_u32_e32 v150, 0x24000, v136
	v_cvt_pk_bf16_f32 v178, v124, v125
	v_cvt_pk_bf16_f32 v179, v126, v127
	v_cvt_pk_bf16_f32 v180, v112, v113
	v_cvt_pk_bf16_f32 v181, v114, v115
	s_nop 1
	v_permlane32_swap_b32_e32 v178, v180
	v_permlane32_swap_b32_e32 v179, v181
	global_store_dwordx4 v136, v[178:181], s[14:15] sc1
	v_cvt_pk_bf16_f32 v182, v120, v121
	v_cvt_pk_bf16_f32 v183, v122, v123
	v_cvt_pk_bf16_f32 v184, v104, v105
	v_cvt_pk_bf16_f32 v185, v106, v107
	s_nop 1
	v_permlane32_swap_b32_e32 v182, v184
	v_permlane32_swap_b32_e32 v183, v185
	global_store_dwordx4 v148, v[182:185], s[14:15] sc1
	v_cvt_pk_bf16_f32 v186, v116, v117
	v_cvt_pk_bf16_f32 v187, v118, v119
	v_cvt_pk_bf16_f32 v188, v100, v101
	v_cvt_pk_bf16_f32 v189, v102, v103
	s_nop 1
	v_permlane32_swap_b32_e32 v186, v188
	v_permlane32_swap_b32_e32 v187, v189
	global_store_dwordx4 v149, v[186:189], s[14:15] sc1
	v_cvt_pk_bf16_f32 v190, v108, v109
	v_cvt_pk_bf16_f32 v191, v110, v111
	v_cvt_pk_bf16_f32 v192, v92, v93
	v_cvt_pk_bf16_f32 v193, v94, v95
	s_nop 1
	v_permlane32_swap_b32_e32 v190, v192
	v_permlane32_swap_b32_e32 v191, v193
	global_store_dwordx4 v150, v[190:193], s[14:15] sc1
	v_cvt_pk_bf16_f32 v198, v96, v97
	v_cvt_pk_bf16_f32 v199, v98, v99
	v_cvt_pk_bf16_f32 v200, v80, v81
	v_cvt_pk_bf16_f32 v201, v82, v83
	s_nop 1
	v_permlane32_swap_b32_e32 v198, v200
	v_permlane32_swap_b32_e32 v199, v201
	global_store_dwordx4 v136, v[198:201], s[14:15] offset:64 sc1
	v_cvt_pk_bf16_f32 v178, v88, v89
	v_cvt_pk_bf16_f32 v179, v90, v91
	v_cvt_pk_bf16_f32 v180, v72, v73
	v_cvt_pk_bf16_f32 v181, v74, v75
	s_nop 1
	v_permlane32_swap_b32_e32 v178, v180
	v_permlane32_swap_b32_e32 v179, v181
	global_store_dwordx4 v148, v[178:181], s[14:15] offset:64 sc1
	v_cvt_pk_bf16_f32 v182, v84, v85
	v_cvt_pk_bf16_f32 v183, v86, v87
	v_cvt_pk_bf16_f32 v184, v68, v69
	v_cvt_pk_bf16_f32 v185, v70, v71
	s_nop 1
	v_permlane32_swap_b32_e32 v182, v184
	v_permlane32_swap_b32_e32 v183, v185
	global_store_dwordx4 v149, v[182:185], s[14:15] offset:64 sc1
	v_cvt_pk_bf16_f32 v186, v76, v77
	v_cvt_pk_bf16_f32 v187, v78, v79
	v_cvt_pk_bf16_f32 v188, v64, v65
	v_cvt_pk_bf16_f32 v189, v66, v67
	s_nop 1
	v_permlane32_swap_b32_e32 v186, v188
	v_permlane32_swap_b32_e32 v187, v189
	global_store_dwordx4 v150, v[186:189], s[14:15] offset:64 sc1
	v_cvt_pk_bf16_f32 v190, v60, v61
	v_cvt_pk_bf16_f32 v191, v62, v63
	v_cvt_pk_bf16_f32 v192, v48, v49
	v_cvt_pk_bf16_f32 v193, v50, v51
	s_nop 1
	v_permlane32_swap_b32_e32 v190, v192
	v_permlane32_swap_b32_e32 v191, v193
	global_store_dwordx4 v136, v[190:193], s[14:15] offset:256 sc1
	v_cvt_pk_bf16_f32 v198, v56, v57
	v_cvt_pk_bf16_f32 v199, v58, v59
	v_cvt_pk_bf16_f32 v200, v40, v41
	v_cvt_pk_bf16_f32 v201, v42, v43
	s_nop 1
	v_permlane32_swap_b32_e32 v198, v200
	v_permlane32_swap_b32_e32 v199, v201
	global_store_dwordx4 v148, v[198:201], s[14:15] offset:256 sc1
	v_cvt_pk_bf16_f32 v178, v52, v53
	v_cvt_pk_bf16_f32 v179, v54, v55
	v_cvt_pk_bf16_f32 v180, v36, v37
	v_cvt_pk_bf16_f32 v181, v38, v39
	s_nop 1
	v_permlane32_swap_b32_e32 v178, v180
	v_permlane32_swap_b32_e32 v179, v181
	global_store_dwordx4 v149, v[178:181], s[14:15] offset:256 sc1
	v_cvt_pk_bf16_f32 v182, v44, v45
	v_cvt_pk_bf16_f32 v183, v46, v47
	v_cvt_pk_bf16_f32 v184, v28, v29
	v_cvt_pk_bf16_f32 v185, v30, v31
	s_nop 1
	v_permlane32_swap_b32_e32 v182, v184
	v_permlane32_swap_b32_e32 v183, v185
	global_store_dwordx4 v150, v[182:185], s[14:15] offset:256 sc1
	v_cvt_pk_bf16_f32 v186, v32, v33
	v_cvt_pk_bf16_f32 v187, v34, v35
	v_cvt_pk_bf16_f32 v188, v16, v17
	v_cvt_pk_bf16_f32 v189, v18, v19
	s_nop 1
	v_permlane32_swap_b32_e32 v186, v188
	v_permlane32_swap_b32_e32 v187, v189
	global_store_dwordx4 v136, v[186:189], s[14:15] offset:320 sc1
	v_cvt_pk_bf16_f32 v190, v24, v25
	v_cvt_pk_bf16_f32 v191, v26, v27
	v_cvt_pk_bf16_f32 v192, v8, v9
	v_cvt_pk_bf16_f32 v193, v10, v11
	s_nop 1
	v_permlane32_swap_b32_e32 v190, v192
	v_permlane32_swap_b32_e32 v191, v193
	global_store_dwordx4 v148, v[190:193], s[14:15] offset:320 sc1
	v_cvt_pk_bf16_f32 v198, v20, v21
	v_cvt_pk_bf16_f32 v199, v22, v23
	v_cvt_pk_bf16_f32 v200, v4, v5
	v_cvt_pk_bf16_f32 v201, v6, v7
	s_nop 1
	v_permlane32_swap_b32_e32 v198, v200
	v_permlane32_swap_b32_e32 v199, v201
	global_store_dwordx4 v149, v[198:201], s[14:15] offset:320 sc1
	v_cvt_pk_bf16_f32 v178, v12, v13
	v_cvt_pk_bf16_f32 v179, v14, v15
	v_cvt_pk_bf16_f32 v180, v0, v1
	v_cvt_pk_bf16_f32 v181, v2, v3
	s_nop 1
	v_permlane32_swap_b32_e32 v178, v180
	v_permlane32_swap_b32_e32 v179, v181
	global_store_dwordx4 v150, v[178:181], s[14:15] offset:320 sc1

; __device__ __forceinline__ unsigned xb_add(unsigned* p, unsigned v) { return __hip_atomic_fetch_add(p, v, __ATOMIC_RELAXED, __HIP_MEMORY_SCOPE_AGENT); }
; __device__ __forceinline__ void xcd_barrier(const XcdBarrier& b) {
;     ...
;         if (old + 1u == (gen + 1u) * nloc) {
;             __builtin_amdgcn_fence(__ATOMIC_RELEASE, "agent");
;             asm volatile("s_waitcnt vmcnt(0)" ::: "memory");
;             const unsigned og = xb_add(&bar[XB_TOP], 1u);
;             const unsigned tg = og / nx;
;             if (og + 1u == (tg + 1u) * nx) xb_add(&bar[XB_TOPGEN], 1u);
.LBB0_325:
	s_andn2_saveexec_b64 s[4:5], s[12:13]
	s_cbranch_execz .LBB0_345
	s_mov_b64 s[12:13], exec
	s_waitcnt lgkmcnt(0)
	v_mbcnt_lo_u32_b32 v1, s12, 0
	v_mbcnt_hi_u32_b32 v1, s13, v1
	v_cmp_eq_u32_e32 vcc, 0, v1
	s_and_saveexec_b64 s[14:15], vcc
	s_cbranch_execz .LBB0_328
	s_bcnt1_i32_b64 s0, s[12:13]
	v_mov_b32_e32 v2, 0xa3000
	v_mov_b32_e32 v3, s0
	global_atomic_add v2, v2, v3, s[24:25] offset:1024 sc0

; __device__ __forceinline__ unsigned pk2(float lo, float hi) { return pg8::cvt_pk_bf16(lo, hi); }
;     __device__ __forceinline__ void operator()(const f32x4 (&acc)[2][2][4][2], const pg8::Unit& u, int wr, int wc, int fr, int fq) const {
;         const int b = u.pm >> 3, colb = u.pn * 256 + wc * 32 + 8 * fq; const int row0 = u.pm * 256 + wr * 64 + fr;
;         const float* mb = mod + b * NMOD;
;         f32x4 g1v[2][2], gm[2][2];
; #pragma unroll
;         for (int bj = 0; bj < 2; ++bj)
; #pragma unroll
;             for (int n = 0; n < 2; ++n) { const int col = colb + 128 * bj + 4 * n; g1v[bj][n] = *(const f32x4*)(mb + 2048 + col);
;                 gm[bj][n] = *(const f32x4*)(n2g + col) * (*(const f32x4*)(mb + 4096 + col) + 1.f); }
; #pragma unroll
;         for (int ai = 0; ai < 2; ++ai) {
;             f32x4 xv[4][2][2];
; #pragma unroll
;             for (int m = 0; m < 4; ++m)
; #pragma unroll
;                 for (int bj = 0; bj < 2; ++bj)
; #pragma unroll
;                     for (int n = 0; n < 2; ++n) xv[m][bj][n] = __builtin_nontemporal_load((const f32x4*)(x + ((unsigned)(row0 + ai * 128 + m * 16) * D_ + colb + 128 * bj + 4 * n)));
; #pragma unroll
;             for (int m = 0; m < 4; ++m) { const unsigned row = (unsigned)(row0 + ai * 128 + m * 16); float ss = 0.f;
; #pragma unroll
;                 for (int bj = 0; bj < 2; ++bj) { f32x4 x1[2]; u32x4 xb;
; #pragma unroll
;                     for (int n = 0; n < 2; ++n) {
;                         x1[n] = xv[m][bj][n] + g1v[bj][n] * acc[ai][bj][m][n];
;                         ss += (x1[n].x * x1[n].x + x1[n].y * x1[n].y) + (x1[n].z * x1[n].z + x1[n].w * x1[n].w); if (n == 0) { xb.x = pk2(x1[0].x, x1[0].y); xb.y = pk2(x1[0].z, x1[0].w); } else { xb.z = pk2(x1[1].x, x1[1].y); xb.w = pk2(x1[1].z, x1[1].w); } x1[n] = x1[n] * gm[bj][n]; }
.LBB0_461:
	s_lshr_b32 s0, s22, 3
	s_lshl_b32 s49, s22, 8
	s_mul_i32 s22, s0, 0x1800
	s_ashr_i32 s23, s22, 31
	s_add_i32 s49, s49, s64
	s_lshl_b64 s[22:23], s[22:23], 2
	s_add_u32 s0, s36, s22
	s_addc_u32 s1, s37, s23
	s_add_u32 s22, s0, 0x2000
	v_lshl_or_b32 v232, s14, 8, v248
	s_addc_u32 s23, s1, 0
	s_add_u32 s54, s0, 0x4000
	v_ashrrev_i32_e32 v233, 31, v232
	s_addc_u32 s55, s1, 0
	v_lshlrev_b64 v[144:145], 2, v[232:233]
	v_lshl_add_u64 v[68:69], s[22:23], 0, v[144:145]
	v_lshl_add_u64 v[152:153], s[34:35], 0, v[144:145]
	v_lshl_add_u64 v[148:149], s[54:55], 0, v[144:145]
	global_load_dwordx4 v[64:67], v[68:69], off offset:16
	global_load_dwordx4 v[80:83], v[68:69], off
	s_nop 0
	global_load_dwordx4 v[68:71], v[152:153], off offset:16
	global_load_dwordx4 v[76:79], v[152:153], off
	global_load_dwordx4 v[144:147], v[148:149], off offset:16
	s_nop 0
	global_load_dwordx4 v[148:151], v[148:149], off
	v_or_b32_e32 v233, s49, v246
	v_lshl_add_u32 v218, v233, 10, v232
	s_lshl_b32 s0, s14, 2
	s_mov_b32 s14, s18
	s_mov_b32 s15, s19
	s_or_b32 s47, s0, s63
	s_waitcnt vmcnt(0)
	v_pk_add_f32 v[150:151], v[150:151], 1.0 op_sel_hi:[1,0]
	s_nop 0
	v_pk_mul_f32 v[242:243], v[78:79], v[150:151]
	v_pk_add_f32 v[78:79], v[144:145], 1.0 op_sel_hi:[1,0]
	v_pk_add_f32 v[148:149], v[148:149], 1.0 op_sel_hi:[1,0]
	v_pk_mul_f32 v[236:237], v[68:69], v[78:79]
	v_or_b32_e32 v68, 0x80, v232
	v_ashrrev_i32_e32 v69, 31, v68
	v_pk_mul_f32 v[244:245], v[76:77], v[148:149]
	v_lshlrev_b64 v[148:149], 2, v[68:69]
	v_pk_add_f32 v[76:77], v[146:147], 1.0 op_sel_hi:[1,0]
	v_lshl_add_u64 v[68:69], s[22:23], 0, v[148:149]
	v_pk_mul_f32 v[234:235], v[70:71], v[76:77]
	global_load_dwordx4 v[68:71], v[68:69], off
	s_nop 0
	global_load_dwordx4 v[144:147], v[152:153], off offset:528
	global_load_dwordx4 v[76:79], v[152:153], off offset:512
	v_lshl_add_u64 v[152:153], s[54:55], 0, v[148:149]
	global_load_dwordx4 v[148:151], v[152:153], off offset:16
	s_nop 0
	global_load_dwordx4 v[152:155], v[152:153], off
	s_waitcnt vmcnt(1)
	v_pk_add_f32 v[148:149], v[148:149], 1.0 op_sel_hi:[1,0]
	s_waitcnt vmcnt(0)
	v_pk_add_f32 v[152:153], v[152:153], 1.0 op_sel_hi:[1,0]
	v_pk_add_f32 v[154:155], v[154:155], 1.0 op_sel_hi:[1,0]
	v_pk_mul_f32 v[240:241], v[76:77], v[152:153]
	v_or_b32_e32 v76, 0x84, v232
	v_ashrrev_i32_e32 v77, 31, v76
	v_lshl_add_u64 v[76:77], v[76:77], 2, s[22:23]
	v_pk_mul_f32 v[230:231], v[144:145], v[148:149]
	v_lshl_add_u64 v[144:145], v[218:219], 2, s[30:31]
	v_pk_mul_f32 v[238:239], v[78:79], v[154:155]
	global_load_dwordx4 v[76:79], v[76:77], off
	s_nop 0
	global_load_dwordx4 v[200:203], v[144:145], off offset:16 nt
	global_load_dwordx4 v[204:207], v[144:145], off nt
	global_load_dwordx4 v[192:195], v[144:145], off offset:528 nt
	global_load_dwordx4 v[196:199], v[144:145], off offset:512 nt
	v_add_u32_e32 v144, 0x4000, v218
	v_mov_b32_e32 v145, v219
	v_lshl_add_u64 v[144:145], v[144:145], 2, s[30:31]
	global_load_dwordx4 v[184:187], v[144:145], off offset:16 nt
	global_load_dwordx4 v[188:191], v[144:145], off nt
	v_add_u32_e32 v144, 0x4080, v218
	v_mov_b32_e32 v145, v219
	v_lshl_add_u64 v[144:145], v[144:145], 2, s[30:31]
	global_load_dwordx4 v[176:179], v[144:145], off offset:16 nt
	global_load_dwordx4 v[180:183], v[144:145], off nt
	v_add_u32_e32 v144, 0x8000, v218
	v_mov_b32_e32 v145, v219
	v_lshl_add_u64 v[144:145], v[144:145], 2, s[30:31]
	global_load_dwordx4 v[168:171], v[144:145], off offset:16 nt
	global_load_dwordx4 v[172:175], v[144:145], off nt
	v_add_u32_e32 v144, 0x8080, v218
	v_mov_b32_e32 v145, v219
	v_lshl_add_u64 v[144:145], v[144:145], 2, s[30:31]
	global_load_dwordx4 v[160:163], v[144:145], off offset:16 nt
	global_load_dwordx4 v[164:167], v[144:145], off nt
	v_add_u32_e32 v144, 0xc000, v218
	v_mov_b32_e32 v145, v219
	v_pk_add_f32 v[150:151], v[150:151], 1.0 op_sel_hi:[1,0]
	v_lshl_add_u64 v[148:149], v[144:145], 2, s[30:31]
	v_pk_mul_f32 v[228:229], v[146:147], v[150:151]
	global_load_dwordx4 v[144:147], v[148:149], off offset:16 nt
	global_load_dwordx4 v[152:155], v[148:149], off nt
	v_add_u32_e32 v148, 0xc080, v218
	v_mov_b32_e32 v149, v219
	v_lshl_add_u64 v[156:157], v[148:149], 2, s[30:31]
	global_load_dwordx4 v[148:151], v[156:157], off offset:16 nt
	s_nop 0
	global_load_dwordx4 v[156:159], v[156:157], off nt
	s_waitcnt vmcnt(15)
	v_pk_fma_f32 v[138:139], v[138:139], v[66:67], v[202:203]
	s_waitcnt vmcnt(14)
	v_pk_fma_f32 v[142:143], v[142:143], v[82:83], v[206:207]
	v_pk_fma_f32 v[204:205], v[140:141], v[80:81], v[204:205]
	v_mul_f32_e32 v141, v143, v143
	v_mul_f32_e32 v140, v205, v205
	v_fmac_f32_e32 v140, v204, v204
	v_fmac_f32_e32 v141, v142, v142
	v_pk_fma_f32 v[136:137], v[136:137], v[64:65], v[200:201]
	v_add_f32_e32 v253, v140, v141
	v_cvt_pk_bf16_f32 v140, v204, v205
	v_cvt_pk_bf16_f32 v141, v142, v143
	v_pk_mul_f32 v[206:207], v[242:243], v[142:143]
	v_mul_f32_e32 v142, v137, v137
	v_mul_f32_e32 v143, v139, v139
	v_fmac_f32_e32 v142, v136, v136
	v_fmac_f32_e32 v143, v138, v138
	v_add_f32_e32 v142, v142, v143
	v_add_f32_e32 v202, v253, v142
	v_cvt_pk_bf16_f32 v142, v136, v137
	v_cvt_pk_bf16_f32 v143, v138, v139
	v_pk_mul_f32 v[200:201], v[234:235], v[138:139]
	v_pk_mul_f32 v[138:139], v[236:237], v[136:137]
	v_pk_mul_f32 v[204:205], v[244:245], v[204:205]
	s_waitcnt vmcnt(12)
; __device__ __forceinline__ unsigned pk2(float lo, float hi) { return pg8::cvt_pk_bf16(lo, hi); }
;     __device__ __forceinline__ void operator()(const f32x4 (&acc)[2][2][4][2], const pg8::Unit& u, int wr, int wc, int fr, int fq) const {
;     ...
;             for (int m = 0; m < 4; ++m) { const unsigned row = (unsigned)(row0 + ai * 128 + m * 16); float ss = 0.f;
; #pragma unroll
;                 for (int bj = 0; bj < 2; ++bj) { f32x4 x1[2]; u32x4 xb;
; #pragma unroll
;                     for (int n = 0; n < 2; ++n) {
;                         x1[n] = xv[m][bj][n] + g1v[bj][n] * acc[ai][bj][m][n];
;                         ss += (x1[n].x * x1[n].x + x1[n].y * x1[n].y) + (x1[n].z * x1[n].z + x1[n].w * x1[n].w); if (n == 0) { xb.x = pk2(x1[0].x, x1[0].y); xb.y = pk2(x1[0].z, x1[0].w); } else { xb.z = pk2(x1[1].x, x1[1].y); xb.w = pk2(x1[1].z, x1[1].w); } x1[n] = x1[n] * gm[bj][n]; }
;                     u32x4 w; w.x = pk2(x1[0].x, x1[0].y); w.y = pk2(x1[0].z, x1[0].w); w.z = pk2(x1[1].x, x1[1].y); w.w = pk2(x1[1].z, x1[1].w);
;                     st16wt(A2, (row * D_ + colb + 128 * bj) * 2u, w);
;                     st16wt(x1b, (row * D_ + colb + 128 * bj) * 2u, xb);
;                     { const unsigned t = row & (S_ - 1); if (t >= 2016u) st16wt(A2tail, (((row >> 11) * 32 + (t - 2016u)) * D_ + colb + 128 * bj) * 2u, w); } }
;                 ss += __shfl_xor(ss, 16); ss += __shfl_xor(ss, 32);
;                 if (fq == 0) rowss[row * 16 + u.pn * 4 + wc] = ss; }
	v_pk_fma_f32 v[134:135], v[134:135], v[70:71], v[198:199]
	v_cvt_pk_bf16_f32 v136, v204, v205
	v_cvt_pk_bf16_f32 v137, v206, v207
	v_cvt_pk_bf16_f32 v138, v138, v139
	v_cvt_pk_bf16_f32 v139, v200, v201
	v_lshlrev_b32_e32 v200, 1, v218
	buffer_store_dwordx4 v[136:139], v200, s[16:19], 0 offen sc1
	v_pk_fma_f32 v[130:131], v[130:131], v[78:79], v[194:195]
	v_pk_fma_f32 v[128:129], v[128:129], v[76:77], v[192:193]
	v_pk_fma_f32 v[136:137], v[132:133], v[68:69], v[196:197]
	v_mul_f32_e32 v133, v135, v135
	v_mul_f32_e32 v132, v137, v137
	v_fmac_f32_e32 v132, v136, v136
	v_fmac_f32_e32 v133, v134, v134
	v_add_f32_e32 v132, v132, v133
	buffer_store_dwordx4 v[140:143], v200, s[12:15], 0 offen sc1
	v_pk_mul_f32 v[138:139], v[238:239], v[134:135]
	s_nop 0
	v_add_f32_e32 v140, v202, v132
	v_cvt_pk_bf16_f32 v132, v136, v137
	v_cvt_pk_bf16_f32 v133, v134, v135
	v_mul_f32_e32 v134, v129, v129
	v_mul_f32_e32 v135, v131, v131
	v_fmac_f32_e32 v134, v128, v128
	v_fmac_f32_e32 v135, v130, v130
	v_add_f32_e32 v134, v134, v135
	v_add_f32_e32 v142, v140, v134
	v_cvt_pk_bf16_f32 v134, v128, v129
	v_cvt_pk_bf16_f32 v135, v130, v131
	v_pk_mul_f32 v[140:141], v[228:229], v[130:131]
	v_pk_mul_f32 v[130:131], v[230:231], v[128:129]
	v_pk_mul_f32 v[136:137], v[240:241], v[136:137]
	s_nop 0
	v_cvt_pk_bf16_f32 v128, v136, v137
	v_cvt_pk_bf16_f32 v129, v138, v139
	v_cvt_pk_bf16_f32 v130, v130, v131
	v_cvt_pk_bf16_f32 v131, v140, v141
	buffer_store_dwordx4 v[128:131], v200, s[16:19], 0 offen offset:256 sc1
	buffer_store_dwordx4 v[132:135], v200, s[12:15], 0 offen offset:256 sc1
	s_nop 0
	v_and_b32_e32 v129, 64, v252
	v_xor_b32_e32 v128, 16, v252
	v_add_u32_e32 v129, 64, v129
	v_cmp_lt_i32_e32 vcc, v128, v129
	v_xor_b32_e32 v131, 32, v252
	s_nop 0
	v_cndmask_b32_e32 v128, v252, v128, vcc
	v_lshlrev_b32_e32 v128, 2, v128
	ds_bpermute_b32 v130, v128, v142
	v_cmp_lt_i32_e32 vcc, v131, v129
	s_waitcnt lgkmcnt(0)
	v_add_f32_e32 v130, v142, v130
	v_cndmask_b32_e32 v129, v252, v131, vcc
	v_lshlrev_b32_e32 v129, 2, v129
	ds_bpermute_b32 v131, v129, v130
	s_and_saveexec_b64 s[22:23], s[8:9]
	s_cbranch_execz .LBB0_463
	v_lshl_add_u32 v132, v233, 4, s47
	v_mov_b32_e32 v133, v219
	v_lshl_add_u64 v[132:133], v[132:133], 2, s[40:41]
	s_waitcnt lgkmcnt(0)
	v_add_f32_e32 v130, v130, v131
	global_store_dword v[132:133], v130, off sc1
.LBB0_463:
	s_or_b64 exec, exec, s[22:23]
	s_waitcnt vmcnt(14)
	v_pk_fma_f32 v[126:127], v[126:127], v[82:83], v[190:191]
	v_pk_fma_f32 v[132:133], v[124:125], v[80:81], v[188:189]
	v_mul_f32_e32 v125, v127, v127
	v_mul_f32_e32 v124, v133, v133
	v_fmac_f32_e32 v124, v132, v132
	v_fmac_f32_e32 v125, v126, v126
	v_pk_fma_f32 v[122:123], v[122:123], v[66:67], v[186:187]
	v_pk_fma_f32 v[120:121], v[120:121], v[64:65], v[184:185]
	v_add_f32_e32 v130, v124, v125
	v_cvt_pk_bf16_f32 v124, v132, v133
	v_cvt_pk_bf16_f32 v125, v126, v127
	v_pk_mul_f32 v[134:135], v[242:243], v[126:127]
	v_mul_f32_e32 v126, v121, v121
	v_mul_f32_e32 v127, v123, v123
	v_fmac_f32_e32 v126, v120, v120
	v_fmac_f32_e32 v127, v122, v122
	v_add_f32_e32 v126, v126, v127
	s_waitcnt lgkmcnt(0)
	v_or_b32_e32 v131, 16, v233
	v_pk_mul_f32 v[132:133], v[244:245], v[132:133]
	v_add_f32_e32 v138, v130, v126
	v_cvt_pk_bf16_f32 v126, v120, v121
	v_cvt_pk_bf16_f32 v127, v122, v123
	v_pk_mul_f32 v[136:137], v[234:235], v[122:123]
	v_pk_mul_f32 v[122:123], v[236:237], v[120:121]
	v_lshlrev_b32_e32 v130, 1, v232
	v_cvt_pk_bf16_f32 v120, v132, v133
	v_cvt_pk_bf16_f32 v121, v134, v135
	v_cvt_pk_bf16_f32 v122, v122, v123
	v_cvt_pk_bf16_f32 v123, v136, v137
	v_lshl_add_u32 v132, v131, 11, v130
	buffer_store_dwordx4 v[120:123], v132, s[16:19], 0 offen sc1
	buffer_store_dwordx4 v[124:127], v132, s[12:15], 0 offen sc1
	s_waitcnt vmcnt(14)
	v_pk_fma_f32 v[118:119], v[118:119], v[70:71], v[182:183]
	v_pk_fma_f32 v[120:121], v[116:117], v[68:69], v[180:181]
	v_mul_f32_e32 v117, v119, v119
	v_mul_f32_e32 v116, v121, v121
	v_fmac_f32_e32 v116, v120, v120
	v_fmac_f32_e32 v117, v118, v118
	v_add_f32_e32 v116, v116, v117
	v_pk_fma_f32 v[114:115], v[114:115], v[78:79], v[178:179]
	v_pk_fma_f32 v[112:113], v[112:113], v[76:77], v[176:177]
	v_add_f32_e32 v124, v138, v116
	v_cvt_pk_bf16_f32 v116, v120, v121
	v_cvt_pk_bf16_f32 v117, v118, v119
	v_pk_mul_f32 v[122:123], v[238:239], v[118:119]
	v_mul_f32_e32 v118, v113, v113
	v_mul_f32_e32 v119, v115, v115
	v_fmac_f32_e32 v118, v112, v112
	v_fmac_f32_e32 v119, v114, v114
	v_add_f32_e32 v118, v118, v119
	v_add_f32_e32 v126, v124, v118
	ds_bpermute_b32 v127, v128, v126
	v_cvt_pk_bf16_f32 v118, v112, v113
	v_pk_mul_f32 v[124:125], v[230:231], v[112:113]
	v_pk_mul_f32 v[120:121], v[240:241], v[120:121]
	v_cvt_pk_bf16_f32 v119, v114, v115
	s_waitcnt lgkmcnt(0)
	v_add_f32_e32 v112, v126, v127
	ds_bpermute_b32 v113, v129, v112
	v_pk_mul_f32 v[114:115], v[228:229], v[114:115]
	v_cvt_pk_bf16_f32 v120, v120, v121
	v_cvt_pk_bf16_f32 v121, v122, v123
	v_cvt_pk_bf16_f32 v122, v124, v125
	s_nop 0
	v_cvt_pk_bf16_f32 v123, v114, v115
	buffer_store_dwordx4 v[120:123], v132, s[16:19], 0 offen offset:256 sc1
	buffer_store_dwordx4 v[116:119], v132, s[12:15], 0 offen offset:256 sc1
	s_and_saveexec_b64 s[14:15], s[8:9]
	s_cbranch_execz .LBB0_465
	v_lshl_add_u32 v114, v131, 4, s47
	v_mov_b32_e32 v115, v219
	v_lshl_add_u64 v[114:115], v[114:115], 2, s[40:41]
	s_waitcnt lgkmcnt(0)
	v_add_f32_e32 v112, v112, v113
	global_store_dword v[114:115], v112, off sc1

; __device__ __forceinline__ unsigned pk2(float lo, float hi) { return pg8::cvt_pk_bf16(lo, hi); }
;     __device__ __forceinline__ void operator()(const f32x4 (&acc)[2][2][4][2], const pg8::Unit& u, int wr, int wc, int fr, int fq) const {
;     ...
;             for (int m = 0; m < 4; ++m) { const unsigned row = (unsigned)(row0 + ai * 128 + m * 16); float ss = 0.f;
; #pragma unroll
;                 for (int bj = 0; bj < 2; ++bj) { f32x4 x1[2]; u32x4 xb;
; #pragma unroll
;                     for (int n = 0; n < 2; ++n) {
;                         x1[n] = xv[m][bj][n] + g1v[bj][n] * acc[ai][bj][m][n];
;                         ss += (x1[n].x * x1[n].x + x1[n].y * x1[n].y) + (x1[n].z * x1[n].z + x1[n].w * x1[n].w); if (n == 0) { xb.x = pk2(x1[0].x, x1[0].y); xb.y = pk2(x1[0].z, x1[0].w); } else { xb.z = pk2(x1[1].x, x1[1].y); xb.w = pk2(x1[1].z, x1[1].w); } x1[n] = x1[n] * gm[bj][n]; }
;                     u32x4 w; w.x = pk2(x1[0].x, x1[0].y); w.y = pk2(x1[0].z, x1[0].w); w.z = pk2(x1[1].x, x1[1].y); w.w = pk2(x1[1].z, x1[1].w);
;                     st16wt(A2, (row * D_ + colb + 128 * bj) * 2u, w);
;                     st16wt(x1b, (row * D_ + colb + 128 * bj) * 2u, xb);
;                     { const unsigned t = row & (S_ - 1); if (t >= 2016u) st16wt(A2tail, (((row >> 11) * 32 + (t - 2016u)) * D_ + colb + 128 * bj) * 2u, w); } }
;                 ss += __shfl_xor(ss, 16); ss += __shfl_xor(ss, 32);
;                 if (fq == 0) rowss[row * 16 + u.pn * 4 + wc] = ss; }
.LBB0_469:
	s_or_b64 exec, exec, s[14:15]
	s_nop 0
	v_mul_f32_e32 v96, v109, v109
	v_mul_f32_e32 v97, v111, v111
	v_fmac_f32_e32 v96, v108, v108
	v_fmac_f32_e32 v97, v110, v110
	v_add_f32_e32 v96, v96, v97
	v_mul_f32_e32 v97, v115, v115
	v_mul_f32_e32 v98, v113, v113
	v_fmac_f32_e32 v97, v114, v114
	v_fmac_f32_e32 v98, v112, v112
	v_add_f32_e32 v97, v97, v98
	v_add_f32_e32 v96, v96, v97
	v_mul_f32_e32 v97, v101, v101
	v_mul_f32_e32 v98, v103, v103
	v_fmac_f32_e32 v97, v100, v100
	v_fmac_f32_e32 v98, v102, v102
	v_add_f32_e32 v97, v97, v98
	v_add_f32_e32 v96, v96, v97
	v_mul_f32_e32 v97, v107, v107
	v_mul_f32_e32 v98, v105, v105
	v_fmac_f32_e32 v97, v106, v106
	v_fmac_f32_e32 v98, v104, v104
	v_add_f32_e32 v97, v97, v98
	v_add_f32_e32 v96, v96, v97
	ds_bpermute_b32 v97, v128, v96
	s_waitcnt lgkmcnt(0)
	v_add_f32_e32 v96, v96, v97
	ds_bpermute_b32 v97, v129, v96
	s_and_saveexec_b64 s[14:15], s[8:9]
	s_cbranch_execz .LBB0_471
	v_lshl_add_u32 v98, v116, 4, s47
	v_mov_b32_e32 v99, v219
	v_lshl_add_u64 v[98:99], v[98:99], 2, s[40:41]
	s_waitcnt lgkmcnt(0)
	v_add_f32_e32 v96, v96, v97
	global_store_dword v[98:99], v96, off sc1

; __device__ __forceinline__ unsigned pk2(float lo, float hi) { return pg8::cvt_pk_bf16(lo, hi); }
;     __device__ __forceinline__ void operator()(const f32x4 (&acc)[2][2][4][2], const pg8::Unit& u, int wr, int wc, int fr, int fq) const {
;     ...
;         for (int ai = 0; ai < 2; ++ai) {
;             f32x4 xv[4][2][2];
; #pragma unroll
;             for (int m = 0; m < 4; ++m)
; #pragma unroll
;                 for (int bj = 0; bj < 2; ++bj)
; #pragma unroll
;                     for (int n = 0; n < 2; ++n) xv[m][bj][n] = __builtin_nontemporal_load((const f32x4*)(x + ((unsigned)(row0 + ai * 128 + m * 16) * D_ + colb + 128 * bj + 4 * n)));
; #pragma unroll
;             for (int m = 0; m < 4; ++m) { const unsigned row = (unsigned)(row0 + ai * 128 + m * 16); float ss = 0.f;
; #pragma unroll
;                 for (int bj = 0; bj < 2; ++bj) { f32x4 x1[2]; u32x4 xb;
; #pragma unroll
;                     for (int n = 0; n < 2; ++n) {
;                         x1[n] = xv[m][bj][n] + g1v[bj][n] * acc[ai][bj][m][n];
;                         ss += (x1[n].x * x1[n].x + x1[n].y * x1[n].y) + (x1[n].z * x1[n].z + x1[n].w * x1[n].w); if (n == 0) { xb.x = pk2(x1[0].x, x1[0].y); xb.y = pk2(x1[0].z, x1[0].w); } else { xb.z = pk2(x1[1].x, x1[1].y); xb.w = pk2(x1[1].z, x1[1].w); } x1[n] = x1[n] * gm[bj][n]; }
;                     u32x4 w; w.x = pk2(x1[0].x, x1[0].y); w.y = pk2(x1[0].z, x1[0].w); w.z = pk2(x1[1].x, x1[1].y); w.w = pk2(x1[1].z, x1[1].w);
;                     st16wt(A2, (row * D_ + colb + 128 * bj) * 2u, w);
;                     st16wt(x1b, (row * D_ + colb + 128 * bj) * 2u, xb);
;                     { const unsigned t = row & (S_ - 1); if (t >= 2016u) st16wt(A2tail, (((row >> 11) * 32 + (t - 2016u)) * D_ + colb + 128 * bj) * 2u, w); } }
;                 ss += __shfl_xor(ss, 16); ss += __shfl_xor(ss, 32);
;                 if (fq == 0) rowss[row * 16 + u.pn * 4 + wc] = ss; }
.LBB0_475:
	s_or_b64 exec, exec, s[14:15]
	s_nop 0
	v_mul_f32_e32 v72, v93, v93
	v_mul_f32_e32 v73, v95, v95
	v_fmac_f32_e32 v72, v92, v92
	v_fmac_f32_e32 v73, v94, v94
	v_add_f32_e32 v72, v72, v73
	v_mul_f32_e32 v73, v99, v99
	v_mul_f32_e32 v74, v97, v97
	v_fmac_f32_e32 v73, v98, v98
	v_fmac_f32_e32 v74, v96, v96
	v_add_f32_e32 v73, v73, v74
	v_add_f32_e32 v72, v72, v73
	v_mul_f32_e32 v73, v85, v85
	v_mul_f32_e32 v74, v87, v87
	v_fmac_f32_e32 v73, v84, v84
	v_fmac_f32_e32 v74, v86, v86
	v_add_f32_e32 v73, v73, v74
	v_add_f32_e32 v72, v72, v73
	v_mul_f32_e32 v73, v91, v91
	v_mul_f32_e32 v74, v89, v89
	v_fmac_f32_e32 v73, v90, v90
	v_fmac_f32_e32 v74, v88, v88
	v_add_f32_e32 v73, v73, v74
	v_add_f32_e32 v72, v72, v73
	ds_bpermute_b32 v73, v128, v72
	s_waitcnt lgkmcnt(0)
	v_add_f32_e32 v72, v72, v73
	ds_bpermute_b32 v73, v129, v72
	s_and_saveexec_b64 s[14:15], s[8:9]
	s_cbranch_execz .LBB0_477
	v_lshl_add_u32 v74, v100, 4, s47
	v_mov_b32_e32 v75, v219
	v_lshl_add_u64 v[74:75], v[74:75], 2, s[40:41]
	s_waitcnt lgkmcnt(0)
	v_add_f32_e32 v72, v72, v73
	global_store_dword v[74:75], v72, off sc1
.LBB0_477:
	s_or_b64 exec, exec, s[14:15]
	v_add_u32_e32 v72, 0x20000, v218
	s_waitcnt lgkmcnt(0)
	v_mov_b32_e32 v73, v219
	v_lshl_add_u64 v[72:73], v[72:73], 2, s[30:31]
	global_load_dwordx4 v[132:135], v[72:73], off offset:16 nt
	global_load_dwordx4 v[136:139], v[72:73], off nt
	v_add_u32_e32 v72, 0x20080, v218
	v_mov_b32_e32 v73, v219
	v_lshl_add_u64 v[72:73], v[72:73], 2, s[30:31]
	global_load_dwordx4 v[140:143], v[72:73], off nt
	global_load_dwordx4 v[144:147], v[72:73], off offset:16 nt
	v_add_u32_e32 v72, 0x24000, v218
	v_mov_b32_e32 v73, v219
	v_add_u32_e32 v74, 0x24080, v218
	v_mov_b32_e32 v75, v219
	v_add_u32_e32 v84, 0x28000, v218
	v_mov_b32_e32 v85, v219
	v_add_u32_e32 v86, 0x28080, v218
	v_mov_b32_e32 v87, v219
	v_add_u32_e32 v88, 0x2c000, v218
	v_mov_b32_e32 v89, v219
	v_add_u32_e32 v218, 0x2c080, v218
	v_lshl_add_u64 v[72:73], v[72:73], 2, s[30:31]
	v_lshl_add_u64 v[74:75], v[74:75], 2, s[30:31]
	v_lshl_add_u64 v[84:85], v[84:85], 2, s[30:31]
	v_lshl_add_u64 v[86:87], v[86:87], 2, s[30:31]
	v_lshl_add_u64 v[92:93], v[88:89], 2, s[30:31]
	v_lshl_add_u64 v[148:149], v[218:219], 2, s[30:31]
	global_load_dwordx4 v[120:123], v[72:73], off offset:16 nt
	global_load_dwordx4 v[124:127], v[72:73], off nt
	global_load_dwordx4 v[112:115], v[74:75], off offset:16 nt
	global_load_dwordx4 v[116:119], v[74:75], off nt
	global_load_dwordx4 v[104:107], v[84:85], off offset:16 nt
	global_load_dwordx4 v[108:111], v[84:85], off nt
	global_load_dwordx4 v[96:99], v[86:87], off offset:16 nt
	global_load_dwordx4 v[100:103], v[86:87], off nt
	global_load_dwordx4 v[88:91], v[92:93], off offset:16 nt
	s_nop 0
	global_load_dwordx4 v[92:95], v[92:93], off nt
	s_nop 0
	global_load_dwordx4 v[72:75], v[148:149], off offset:16 nt
	global_load_dwordx4 v[84:87], v[148:149], off nt
	v_add_u32_e32 v131, 0x80, v233
	v_lshl_add_u32 v148, v131, 11, v130
	s_mov_b32 s14, s18
	s_mov_b32 s15, s19
	s_waitcnt vmcnt(15)
	v_pk_fma_f32 v[58:59], v[58:59], v[66:67], v[134:135]
	s_waitcnt vmcnt(14)
	v_pk_fma_f32 v[62:63], v[62:63], v[82:83], v[138:139]
	v_pk_fma_f32 v[60:61], v[60:61], v[80:81], v[136:137]
	v_pk_fma_f32 v[56:57], v[56:57], v[64:65], v[132:133]
	s_waitcnt vmcnt(13)
	v_pk_fma_f32 v[132:133], v[54:55], v[70:71], v[142:143]
	v_pk_fma_f32 v[134:135], v[52:53], v[68:69], v[140:141]
	s_waitcnt vmcnt(12)
	v_pk_fma_f32 v[138:139], v[48:49], v[76:77], v[144:145]
	v_mul_f32_e32 v149, v61, v61
	v_mul_f32_e32 v150, v63, v63
	v_cvt_pk_bf16_f32 v48, v60, v61
	v_cvt_pk_bf16_f32 v49, v62, v63
	v_pk_mul_f32 v[54:55], v[242:243], v[62:63]
	v_pk_mul_f32 v[52:53], v[244:245], v[60:61]
	v_mul_f32_e32 v61, v57, v57
	v_mul_f32_e32 v63, v59, v59
	v_pk_fma_f32 v[136:137], v[50:51], v[78:79], v[146:147]
	v_cvt_pk_bf16_f32 v50, v56, v57
	v_cvt_pk_bf16_f32 v51, v58, v59
	v_pk_mul_f32 v[140:141], v[234:235], v[58:59]
	v_pk_mul_f32 v[142:143], v[236:237], v[56:57]
	v_mul_f32_e32 v57, v135, v135
	v_mul_f32_e32 v59, v133, v133
	v_fmac_f32_e32 v149, v60, v60
	v_fmac_f32_e32 v150, v62, v62
	v_fmac_f32_e32 v61, v56, v56
	v_fmac_f32_e32 v63, v58, v58
	v_cvt_pk_bf16_f32 v52, v52, v53
	v_cvt_pk_bf16_f32 v53, v54, v55
	v_cvt_pk_bf16_f32 v54, v142, v143
	v_cvt_pk_bf16_f32 v55, v140, v141
	v_fmac_f32_e32 v57, v134, v134
	v_fmac_f32_e32 v59, v132, v132
	v_add_f32_e32 v56, v149, v150
	v_add_f32_e32 v58, v61, v63
	buffer_store_dwordx4 v[52:55], v148, s[16:19], 0 offen sc1
	buffer_store_dwordx4 v[48:51], v148, s[12:15], 0 offen sc1
	v_mul_f32_e32 v151, v139, v139
	v_fmac_f32_e32 v151, v138, v138
	v_add_f32_e32 v48, v57, v59
	v_add_f32_e32 v49, v56, v58
	v_add_f32_e32 v48, v49, v48
	v_mul_f32_e32 v49, v137, v137
	v_fmac_f32_e32 v49, v136, v136
	v_add_f32_e32 v49, v151, v49
	v_add_f32_e32 v48, v48, v49
	ds_bpermute_b32 v49, v128, v48
	v_pk_mul_f32 v[56:57], v[230:231], v[138:139]
	v_pk_mul_f32 v[144:145], v[238:239], v[132:133]
	v_pk_mul_f32 v[146:147], v[240:241], v[134:135]
	v_cvt_pk_bf16_f32 v50, v134, v135
	s_waitcnt lgkmcnt(0)
	v_add_f32_e32 v48, v48, v49
	ds_bpermute_b32 v49, v129, v48
	v_cvt_pk_bf16_f32 v51, v132, v133
	v_cvt_pk_bf16_f32 v52, v138, v139
	v_cvt_pk_bf16_f32 v53, v136, v137
	v_pk_mul_f32 v[58:59], v[228:229], v[136:137]
	v_cvt_pk_bf16_f32 v54, v146, v147
	v_cvt_pk_bf16_f32 v55, v144, v145
	v_cvt_pk_bf16_f32 v56, v56, v57
	s_nop 0
	v_cvt_pk_bf16_f32 v57, v58, v59
	buffer_store_dwordx4 v[54:57], v148, s[16:19], 0 offen offset:256 sc1
	buffer_store_dwordx4 v[50:53], v148, s[12:15], 0 offen offset:256 sc1
	s_and_saveexec_b64 s[22:23], s[8:9]
	s_cbranch_execz .LBB0_479
	v_lshl_add_u32 v218, v131, 4, s47
	v_lshl_add_u64 v[50:51], v[218:219], 2, s[40:41]
	s_waitcnt lgkmcnt(0)
	v_add_f32_e32 v48, v48, v49
	global_store_dword v[50:51], v48, off sc1
; __device__ __forceinline__ unsigned pk2(float lo, float hi) { return pg8::cvt_pk_bf16(lo, hi); }
;     __device__ __forceinline__ void operator()(const f32x4 (&acc)[2][2][4][2], const pg8::Unit& u, int wr, int wc, int fr, int fq) const {
;     ...
;             for (int m = 0; m < 4; ++m) { const unsigned row = (unsigned)(row0 + ai * 128 + m * 16); float ss = 0.f;
; #pragma unroll
;                 for (int bj = 0; bj < 2; ++bj) { f32x4 x1[2]; u32x4 xb;
; #pragma unroll
;                     for (int n = 0; n < 2; ++n) {
;                         x1[n] = xv[m][bj][n] + g1v[bj][n] * acc[ai][bj][m][n];
;                         ss += (x1[n].x * x1[n].x + x1[n].y * x1[n].y) + (x1[n].z * x1[n].z + x1[n].w * x1[n].w); if (n == 0) { xb.x = pk2(x1[0].x, x1[0].y); xb.y = pk2(x1[0].z, x1[0].w); } else { xb.z = pk2(x1[1].x, x1[1].y); xb.w = pk2(x1[1].z, x1[1].w); } x1[n] = x1[n] * gm[bj][n]; }
;                     u32x4 w; w.x = pk2(x1[0].x, x1[0].y); w.y = pk2(x1[0].z, x1[0].w); w.z = pk2(x1[1].x, x1[1].y); w.w = pk2(x1[1].z, x1[1].w);
;                     st16wt(A2, (row * D_ + colb + 128 * bj) * 2u, w);
;                     st16wt(x1b, (row * D_ + colb + 128 * bj) * 2u, xb);
;                     { const unsigned t = row & (S_ - 1); if (t >= 2016u) st16wt(A2tail, (((row >> 11) * 32 + (t - 2016u)) * D_ + colb + 128 * bj) * 2u, w); } }
;                 ss += __shfl_xor(ss, 16); ss += __shfl_xor(ss, 32);
;                 if (fq == 0) rowss[row * 16 + u.pn * 4 + wc] = ss; }
.LBB0_479:
	s_or_b64 exec, exec, s[22:23]
	s_waitcnt vmcnt(14)
	v_pk_fma_f32 v[46:47], v[46:47], v[82:83], v[126:127]
	v_pk_fma_f32 v[50:51], v[44:45], v[80:81], v[124:125]
	v_mul_f32_e32 v45, v47, v47
	v_mul_f32_e32 v44, v51, v51
	v_fmac_f32_e32 v44, v50, v50
	v_fmac_f32_e32 v45, v46, v46
	v_pk_fma_f32 v[42:43], v[42:43], v[66:67], v[122:123]
	v_pk_fma_f32 v[40:41], v[40:41], v[64:65], v[120:121]
	s_waitcnt lgkmcnt(0)
	v_add_f32_e32 v49, v44, v45
	v_cvt_pk_bf16_f32 v44, v50, v51
	v_cvt_pk_bf16_f32 v45, v46, v47
	v_pk_mul_f32 v[52:53], v[242:243], v[46:47]
	v_mul_f32_e32 v46, v41, v41
	v_mul_f32_e32 v47, v43, v43
	v_fmac_f32_e32 v46, v40, v40
	v_fmac_f32_e32 v47, v42, v42
	v_add_f32_e32 v46, v46, v47
	v_add_u32_e32 v48, 0x90, v233
	v_pk_mul_f32 v[50:51], v[244:245], v[50:51]
	v_add_f32_e32 v49, v49, v46
	v_cvt_pk_bf16_f32 v46, v40, v41
	v_cvt_pk_bf16_f32 v47, v42, v43
	v_pk_mul_f32 v[54:55], v[234:235], v[42:43]
	v_pk_mul_f32 v[42:43], v[236:237], v[40:41]
	v_cvt_pk_bf16_f32 v40, v50, v51
	v_cvt_pk_bf16_f32 v41, v52, v53
	v_lshl_add_u32 v50, v48, 11, v130
	v_cvt_pk_bf16_f32 v42, v42, v43
	v_cvt_pk_bf16_f32 v43, v54, v55
	buffer_store_dwordx4 v[40:43], v50, s[16:19], 0 offen sc1
	buffer_store_dwordx4 v[44:47], v50, s[12:15], 0 offen sc1
	s_waitcnt vmcnt(14)
	v_pk_fma_f32 v[38:39], v[38:39], v[70:71], v[118:119]
	v_pk_fma_f32 v[40:41], v[36:37], v[68:69], v[116:117]
	v_mul_f32_e32 v37, v39, v39
	v_mul_f32_e32 v36, v41, v41
	v_fmac_f32_e32 v36, v40, v40
	v_fmac_f32_e32 v37, v38, v38
	v_add_f32_e32 v36, v36, v37
	v_pk_fma_f32 v[34:35], v[34:35], v[78:79], v[114:115]
	v_pk_fma_f32 v[32:33], v[32:33], v[76:77], v[112:113]
	v_add_f32_e32 v44, v49, v36
	v_cvt_pk_bf16_f32 v36, v40, v41
	v_cvt_pk_bf16_f32 v37, v38, v39
	v_pk_mul_f32 v[42:43], v[238:239], v[38:39]
	v_mul_f32_e32 v38, v33, v33
	v_mul_f32_e32 v39, v35, v35
	v_fmac_f32_e32 v38, v32, v32
	v_fmac_f32_e32 v39, v34, v34
	v_add_f32_e32 v38, v38, v39
	v_add_f32_e32 v46, v44, v38
	ds_bpermute_b32 v47, v128, v46
	v_cvt_pk_bf16_f32 v38, v32, v33
	v_pk_mul_f32 v[44:45], v[230:231], v[32:33]
	v_pk_mul_f32 v[40:41], v[240:241], v[40:41]
	v_cvt_pk_bf16_f32 v39, v34, v35
	s_waitcnt lgkmcnt(0)
	v_add_f32_e32 v32, v46, v47
	ds_bpermute_b32 v33, v129, v32
	v_pk_mul_f32 v[34:35], v[228:229], v[34:35]
	v_cvt_pk_bf16_f32 v40, v40, v41
	v_cvt_pk_bf16_f32 v41, v42, v43
	v_cvt_pk_bf16_f32 v42, v44, v45
	s_nop 0
	v_cvt_pk_bf16_f32 v43, v34, v35
	buffer_store_dwordx4 v[40:43], v50, s[16:19], 0 offen offset:256 sc1
	buffer_store_dwordx4 v[36:39], v50, s[12:15], 0 offen offset:256 sc1
	s_and_saveexec_b64 s[14:15], s[8:9]
	s_cbranch_execz .LBB0_481
	v_lshl_add_u32 v218, v48, 4, s47
	v_lshl_add_u64 v[34:35], v[218:219], 2, s[40:41]
	s_waitcnt lgkmcnt(0)
	v_add_f32_e32 v32, v32, v33
	global_store_dword v[34:35], v32, off sc1

; __device__ __forceinline__ unsigned pk2(float lo, float hi) { return pg8::cvt_pk_bf16(lo, hi); }
;     __device__ __forceinline__ void operator()(const f32x4 (&acc)[2][2][4][2], const pg8::Unit& u, int wr, int wc, int fr, int fq) const {
;     ...
;             for (int m = 0; m < 4; ++m) { const unsigned row = (unsigned)(row0 + ai * 128 + m * 16); float ss = 0.f;
; #pragma unroll
;                 for (int bj = 0; bj < 2; ++bj) { f32x4 x1[2]; u32x4 xb;
; #pragma unroll
;                     for (int n = 0; n < 2; ++n) {
;                         x1[n] = xv[m][bj][n] + g1v[bj][n] * acc[ai][bj][m][n];
;                         ss += (x1[n].x * x1[n].x + x1[n].y * x1[n].y) + (x1[n].z * x1[n].z + x1[n].w * x1[n].w); if (n == 0) { xb.x = pk2(x1[0].x, x1[0].y); xb.y = pk2(x1[0].z, x1[0].w); } else { xb.z = pk2(x1[1].x, x1[1].y); xb.w = pk2(x1[1].z, x1[1].w); } x1[n] = x1[n] * gm[bj][n]; }
;                     u32x4 w; w.x = pk2(x1[0].x, x1[0].y); w.y = pk2(x1[0].z, x1[0].w); w.z = pk2(x1[1].x, x1[1].y); w.w = pk2(x1[1].z, x1[1].w);
;                     st16wt(A2, (row * D_ + colb + 128 * bj) * 2u, w);
;                     st16wt(x1b, (row * D_ + colb + 128 * bj) * 2u, xb);
;                     { const unsigned t = row & (S_ - 1); if (t >= 2016u) st16wt(A2tail, (((row >> 11) * 32 + (t - 2016u)) * D_ + colb + 128 * bj) * 2u, w); } }
;                 ss += __shfl_xor(ss, 16); ss += __shfl_xor(ss, 32);
;                 if (fq == 0) rowss[row * 16 + u.pn * 4 + wc] = ss; }
.LBB0_485:
	s_or_b64 exec, exec, s[14:15]
	s_nop 0
	v_mul_f32_e32 v16, v29, v29
	v_mul_f32_e32 v17, v31, v31
	v_fmac_f32_e32 v16, v28, v28
	v_fmac_f32_e32 v17, v30, v30
	v_add_f32_e32 v16, v16, v17
	v_mul_f32_e32 v17, v35, v35
	v_mul_f32_e32 v18, v33, v33
	v_fmac_f32_e32 v17, v34, v34
	v_fmac_f32_e32 v18, v32, v32
	v_add_f32_e32 v17, v17, v18
	v_add_f32_e32 v16, v16, v17
	v_mul_f32_e32 v17, v21, v21
	v_mul_f32_e32 v18, v23, v23
	v_fmac_f32_e32 v17, v20, v20
	v_fmac_f32_e32 v18, v22, v22
	v_add_f32_e32 v17, v17, v18
	v_add_f32_e32 v16, v16, v17
	v_mul_f32_e32 v17, v27, v27
	v_mul_f32_e32 v18, v25, v25
	v_fmac_f32_e32 v17, v26, v26
	v_fmac_f32_e32 v18, v24, v24
	v_add_f32_e32 v17, v17, v18
	v_add_f32_e32 v16, v16, v17
	ds_bpermute_b32 v17, v128, v16
	s_waitcnt lgkmcnt(0)
	v_add_f32_e32 v16, v16, v17
	ds_bpermute_b32 v17, v129, v16
	s_and_saveexec_b64 s[14:15], s[8:9]
	s_cbranch_execz .LBB0_487
	v_lshl_add_u32 v218, v37, 4, s47
	v_lshl_add_u64 v[18:19], v[218:219], 2, s[40:41]
	s_waitcnt lgkmcnt(0)
	v_add_f32_e32 v16, v16, v17
	global_store_dword v[18:19], v16, off sc1

; __device__ __forceinline__ unsigned pk2(float lo, float hi) { return pg8::cvt_pk_bf16(lo, hi); }
;     __device__ __forceinline__ void operator()(const f32x4 (&acc)[2][2][4][2], const pg8::Unit& u, int wr, int wc, int fr, int fq) const {
;     ...
;             for (int m = 0; m < 4; ++m) { const unsigned row = (unsigned)(row0 + ai * 128 + m * 16); float ss = 0.f;
; #pragma unroll
;                 for (int bj = 0; bj < 2; ++bj) { f32x4 x1[2]; u32x4 xb;
; #pragma unroll
;                     for (int n = 0; n < 2; ++n) {
;                         x1[n] = xv[m][bj][n] + g1v[bj][n] * acc[ai][bj][m][n];
;                         ss += (x1[n].x * x1[n].x + x1[n].y * x1[n].y) + (x1[n].z * x1[n].z + x1[n].w * x1[n].w); if (n == 0) { xb.x = pk2(x1[0].x, x1[0].y); xb.y = pk2(x1[0].z, x1[0].w); } else { xb.z = pk2(x1[1].x, x1[1].y); xb.w = pk2(x1[1].z, x1[1].w); } x1[n] = x1[n] * gm[bj][n]; }
;                     u32x4 w; w.x = pk2(x1[0].x, x1[0].y); w.y = pk2(x1[0].z, x1[0].w); w.z = pk2(x1[1].x, x1[1].y); w.w = pk2(x1[1].z, x1[1].w);
;                     st16wt(A2, (row * D_ + colb + 128 * bj) * 2u, w);
;                     st16wt(x1b, (row * D_ + colb + 128 * bj) * 2u, xb);
;                     { const unsigned t = row & (S_ - 1); if (t >= 2016u) st16wt(A2tail, (((row >> 11) * 32 + (t - 2016u)) * D_ + colb + 128 * bj) * 2u, w); } }
;                 ss += __shfl_xor(ss, 16); ss += __shfl_xor(ss, 32);
;                 if (fq == 0) rowss[row * 16 + u.pn * 4 + wc] = ss; }
.LBB0_491:
	s_or_b64 exec, exec, s[14:15]
	s_nop 0
	v_mul_f32_e32 v0, v13, v13
	v_mul_f32_e32 v1, v15, v15
	v_fmac_f32_e32 v0, v12, v12
	v_fmac_f32_e32 v1, v14, v14
	v_add_f32_e32 v0, v0, v1
	v_mul_f32_e32 v1, v19, v19
	v_mul_f32_e32 v2, v17, v17
	v_fmac_f32_e32 v1, v18, v18
	v_fmac_f32_e32 v2, v16, v16
	v_add_f32_e32 v1, v1, v2
	v_add_f32_e32 v0, v0, v1
	v_mul_f32_e32 v1, v5, v5
	v_mul_f32_e32 v2, v7, v7
	v_fmac_f32_e32 v1, v4, v4
	v_fmac_f32_e32 v2, v6, v6
	v_add_f32_e32 v1, v1, v2
	v_add_f32_e32 v0, v0, v1
	v_mul_f32_e32 v1, v11, v11
	v_mul_f32_e32 v2, v9, v9
	v_fmac_f32_e32 v1, v10, v10
	v_fmac_f32_e32 v2, v8, v8
	v_add_f32_e32 v1, v1, v2
	v_add_f32_e32 v0, v0, v1
	ds_bpermute_b32 v1, v128, v0
	s_waitcnt lgkmcnt(0)
	v_add_f32_e32 v0, v0, v1
	ds_bpermute_b32 v1, v129, v0
	s_and_saveexec_b64 s[14:15], s[8:9]
	s_cbranch_execz .LBB0_493
	v_lshl_add_u32 v218, v20, 4, s47
	v_lshl_add_u64 v[2:3], v[218:219], 2, s[40:41]
	s_waitcnt lgkmcnt(0)
	v_add_f32_e32 v0, v0, v1
	global_store_dword v[2:3], v0, off sc1
